# speedup vs baseline: 1.0207x; 1.0030x over previous
; __device__ __forceinline__ float silu_f(float v) { return v / (1.f + __expf(-v)); }
; __device__ void mod_item(const Params& p, int it, unsigned char* smem) {
;     ...
;     for (int i = tid; i < 2048; i += NTHREADS) sc[i] = silu_f(p.c[i]);
.LBB0_50:
	global_load_dword v30, v[6:7], off
	global_load_dword v31, v[6:7], off offset:2048
	v_lshl_add_u64 v[14:15], v[6:7], 0, s[4:5]
	v_lshl_add_u64 v[14:15], v[14:15], 0, s[4:5]
	global_load_dword v32, v[14:15], off
	global_load_dword v33, v[14:15], off offset:2048
	s_waitcnt vmcnt(3)
	v_mul_f32_e32 v8, 0xbfb8aa3b, v30
	v_exp_f32_e32 v8, v8
	s_nop 0
	v_add_f32_e32 v8, 1.0, v8
	v_div_scale_f32 v9, s[14:15], v8, v8, v30
	v_rcp_f32_e32 v10, v9
	v_div_scale_f32 v11, vcc, v30, v8, v30
	v_fma_f32 v12, -v9, v10, 1.0
	v_fmac_f32_e32 v10, v12, v10
	v_mul_f32_e32 v12, v11, v10
	v_fma_f32 v13, -v9, v12, v11
	v_fmac_f32_e32 v12, v13, v10
	v_fma_f32 v9, -v9, v12, v11
	v_div_fmas_f32 v9, v9, v10, v12
	v_div_fixup_f32 v5, v9, v8, v30
	ds_write_b32 v2, v5
	s_waitcnt vmcnt(2)
	v_mul_f32_e32 v8, 0xbfb8aa3b, v31
	v_exp_f32_e32 v8, v8
	s_nop 0
	v_add_f32_e32 v8, 1.0, v8
	v_div_scale_f32 v9, s[14:15], v8, v8, v31
	v_rcp_f32_e32 v10, v9
	v_div_scale_f32 v11, vcc, v31, v8, v31
	v_fma_f32 v12, -v9, v10, 1.0
	v_fmac_f32_e32 v10, v12, v10
	v_mul_f32_e32 v12, v11, v10
	v_fma_f32 v13, -v9, v12, v11
	v_fmac_f32_e32 v12, v13, v10
	v_fma_f32 v9, -v9, v12, v11
	v_div_fmas_f32 v9, v9, v10, v12
	v_div_fixup_f32 v5, v9, v8, v31
	ds_write_b32 v2, v5 offset:2048
	s_waitcnt vmcnt(1)
	v_mul_f32_e32 v8, 0xbfb8aa3b, v32
	v_exp_f32_e32 v8, v8
	s_nop 0
	v_add_f32_e32 v8, 1.0, v8
	v_div_scale_f32 v9, s[14:15], v8, v8, v32
	v_rcp_f32_e32 v10, v9
	v_div_scale_f32 v11, vcc, v32, v8, v32
	v_fma_f32 v12, -v9, v10, 1.0
	v_fmac_f32_e32 v10, v12, v10
	v_mul_f32_e32 v12, v11, v10
	v_fma_f32 v13, -v9, v12, v11
	v_fmac_f32_e32 v12, v13, v10
	v_fma_f32 v9, -v9, v12, v11
	v_div_fmas_f32 v9, v9, v10, v12
	v_div_fixup_f32 v5, v9, v8, v32
	ds_write_b32 v2, v5 offset:4096
	s_waitcnt vmcnt(0)
	v_mul_f32_e32 v8, 0xbfb8aa3b, v33
	v_exp_f32_e32 v8, v8
	s_nop 0
	v_add_f32_e32 v8, 1.0, v8
	v_div_scale_f32 v9, s[14:15], v8, v8, v33
	v_rcp_f32_e32 v10, v9
	v_div_scale_f32 v11, vcc, v33, v8, v33
	v_fma_f32 v12, -v9, v10, 1.0
	v_fmac_f32_e32 v10, v12, v10
	v_mul_f32_e32 v12, v11, v10
	v_fma_f32 v13, -v9, v12, v11
	v_fmac_f32_e32 v12, v13, v10
	v_fma_f32 v9, -v9, v12, v11
	v_div_fmas_f32 v9, v9, v10, v12
	v_div_fixup_f32 v5, v9, v8, v33
	ds_write_b32 v2, v5 offset:6144

; __device__ void mod_item(const Params& p, int it, unsigned char* smem) {
;     ...
; #pragma unroll 8
;     for (int k = kq; k < D; k += 8) {
;         float wv = w[(size_t)k * (NMOD * D)];
;         a0 += sc[k] * wv; a1 += sc[1024 + k] * wv;
;     }
.LBB0_58:
	v_lshl_add_u64 v[26:27], v[22:23], 0, v[2:3]
	v_lshl_add_u64 v[28:29], v[20:21], 0, v[2:3]
	v_lshl_add_u64 v[30:31], v[18:19], 0, v[2:3]
	v_lshl_add_u64 v[32:33], v[16:17], 0, v[2:3]
	v_lshl_add_u64 v[34:35], v[14:15], 0, v[2:3]
	v_lshl_add_u64 v[36:37], v[12:13], 0, v[2:3]
	v_lshl_add_u64 v[38:39], v[10:11], 0, v[2:3]
	v_lshl_add_u64 v[40:41], v[8:9], 0, v[2:3]
	global_load_dword v134, v[26:27], off
	global_load_dword v136, v[28:29], off
	global_load_dword v138, v[30:31], off
	global_load_dword v140, v[32:33], off
	global_load_dword v142, v[34:35], off
	global_load_dword v144, v[36:37], off
	global_load_dword v146, v[38:39], off
	global_load_dword v148, v[40:41], off
	v_lshl_add_u64 v[22:23], v[22:23], 0, s[8:9]
	v_lshl_add_u64 v[20:21], v[20:21], 0, s[8:9]
	v_lshl_add_u64 v[18:19], v[18:19], 0, s[8:9]
	v_lshl_add_u64 v[16:17], v[16:17], 0, s[8:9]
	v_lshl_add_u64 v[14:15], v[14:15], 0, s[8:9]
	v_lshl_add_u64 v[12:13], v[12:13], 0, s[8:9]
	v_lshl_add_u64 v[10:11], v[10:11], 0, s[8:9]
	v_lshl_add_u64 v[8:9], v[8:9], 0, s[8:9]
	v_lshl_add_u64 v[26:27], v[22:23], 0, v[2:3]
	v_lshl_add_u64 v[28:29], v[20:21], 0, v[2:3]
	v_lshl_add_u64 v[30:31], v[18:19], 0, v[2:3]
	v_lshl_add_u64 v[32:33], v[16:17], 0, v[2:3]
	v_lshl_add_u64 v[34:35], v[14:15], 0, v[2:3]
	v_lshl_add_u64 v[36:37], v[12:13], 0, v[2:3]
	v_lshl_add_u64 v[38:39], v[10:11], 0, v[2:3]
	v_lshl_add_u64 v[40:41], v[8:9], 0, v[2:3]
	global_load_dword v150, v[26:27], off
	global_load_dword v152, v[28:29], off
	global_load_dword v154, v[30:31], off
	global_load_dword v156, v[32:33], off
	global_load_dword v158, v[34:35], off
	global_load_dword v160, v[36:37], off
	global_load_dword v162, v[38:39], off
	global_load_dword v164, v[40:41], off
	v_lshl_add_u64 v[22:23], v[22:23], 0, s[8:9]
	v_lshl_add_u64 v[20:21], v[20:21], 0, s[8:9]
	v_lshl_add_u64 v[18:19], v[18:19], 0, s[8:9]
	v_lshl_add_u64 v[16:17], v[16:17], 0, s[8:9]
	v_lshl_add_u64 v[14:15], v[14:15], 0, s[8:9]
	v_lshl_add_u64 v[12:13], v[12:13], 0, s[8:9]
	v_lshl_add_u64 v[10:11], v[10:11], 0, s[8:9]
	v_lshl_add_u64 v[8:9], v[8:9], 0, s[8:9]
	v_lshl_add_u64 v[26:27], v[22:23], 0, v[2:3]
	v_lshl_add_u64 v[28:29], v[20:21], 0, v[2:3]
	v_lshl_add_u64 v[30:31], v[18:19], 0, v[2:3]
	v_lshl_add_u64 v[32:33], v[16:17], 0, v[2:3]
	v_lshl_add_u64 v[34:35], v[14:15], 0, v[2:3]
	v_lshl_add_u64 v[36:37], v[12:13], 0, v[2:3]
	v_lshl_add_u64 v[38:39], v[10:11], 0, v[2:3]
	v_lshl_add_u64 v[40:41], v[8:9], 0, v[2:3]
	global_load_dword v166, v[26:27], off
	global_load_dword v168, v[28:29], off
	global_load_dword v170, v[30:31], off
	global_load_dword v172, v[32:33], off
	global_load_dword v174, v[34:35], off
	global_load_dword v176, v[36:37], off
	global_load_dword v178, v[38:39], off
	global_load_dword v180, v[40:41], off
	v_lshl_add_u64 v[22:23], v[22:23], 0, s[8:9]
	v_lshl_add_u64 v[20:21], v[20:21], 0, s[8:9]
	v_lshl_add_u64 v[18:19], v[18:19], 0, s[8:9]
	v_lshl_add_u64 v[16:17], v[16:17], 0, s[8:9]
	v_lshl_add_u64 v[14:15], v[14:15], 0, s[8:9]
	v_lshl_add_u64 v[12:13], v[12:13], 0, s[8:9]
	v_lshl_add_u64 v[10:11], v[10:11], 0, s[8:9]
	v_lshl_add_u64 v[8:9], v[8:9], 0, s[8:9]
	v_lshl_add_u64 v[26:27], v[22:23], 0, v[2:3]
	v_lshl_add_u64 v[28:29], v[20:21], 0, v[2:3]
	v_lshl_add_u64 v[30:31], v[18:19], 0, v[2:3]
	v_lshl_add_u64 v[32:33], v[16:17], 0, v[2:3]
	v_lshl_add_u64 v[34:35], v[14:15], 0, v[2:3]
	v_lshl_add_u64 v[36:37], v[12:13], 0, v[2:3]
	v_lshl_add_u64 v[38:39], v[10:11], 0, v[2:3]
	v_lshl_add_u64 v[40:41], v[8:9], 0, v[2:3]
	global_load_dword v182, v[26:27], off
	global_load_dword v184, v[28:29], off
	global_load_dword v186, v[30:31], off
	global_load_dword v190, v[32:33], off
	global_load_dword v192, v[34:35], off
	global_load_dword v194, v[36:37], off
	global_load_dword v196, v[38:39], off
	global_load_dword v198, v[40:41], off
	v_lshl_add_u64 v[22:23], v[22:23], 0, s[8:9]
	v_lshl_add_u64 v[20:21], v[20:21], 0, s[8:9]
	v_lshl_add_u64 v[18:19], v[18:19], 0, s[8:9]
	v_lshl_add_u64 v[16:17], v[16:17], 0, s[8:9]
	v_lshl_add_u64 v[14:15], v[14:15], 0, s[8:9]
	v_lshl_add_u64 v[12:13], v[12:13], 0, s[8:9]
	v_lshl_add_u64 v[10:11], v[10:11], 0, s[8:9]
	v_lshl_add_u64 v[8:9], v[8:9], 0, s[8:9]
	v_add_u32_e32 v24, 0x100, v24
	v_cmp_lt_i32_e32 vcc, s38, v24
	s_or_b64 s[16:17], vcc, s[16:17]
	v_add_u32_e32 v27, 0x1000, v25
	ds_read2_b32 v[42:43], v25 offset1:8
	ds_read2_b32 v[44:45], v25 offset0:16 offset1:24
	ds_read2_b32 v[46:47], v25 offset0:32 offset1:40
	ds_read2_b32 v[48:49], v25 offset0:48 offset1:56
	ds_read2_b32 v[50:51], v27 offset1:8
	ds_read2_b32 v[52:53], v27 offset0:16 offset1:24
	ds_read2_b32 v[54:55], v27 offset0:32 offset1:40
	ds_read2_b32 v[56:57], v27 offset0:48 offset1:56
	v_add_u32_e32 v25, 0x100, v25
	s_waitcnt lgkmcnt(0)
	v_mov_b32_e32 v59, v42
	v_mov_b32_e32 v58, v50
	v_mov_b32_e32 v42, v51
	v_mov_b32_e32 v61, v44
	v_mov_b32_e32 v60, v52
	v_mov_b32_e32 v44, v53
	v_mov_b32_e32 v63, v46
	v_mov_b32_e32 v62, v54
	v_mov_b32_e32 v46, v55
	v_mov_b32_e32 v65, v48
	v_mov_b32_e32 v64, v56
	v_mov_b32_e32 v48, v57
	s_waitcnt vmcnt(31)
	v_pk_fma_f32 v[6:7], v[134:135], v[58:59], v[6:7] op_sel_hi:[0,1,1]
	s_waitcnt vmcnt(30)
; __device__ void mod_item(const Params& p, int it, unsigned char* smem) {
;     ...
; #pragma unroll 8
;     for (int k = kq; k < D; k += 8) {
;         float wv = w[(size_t)k * (NMOD * D)];
;         a0 += sc[k] * wv; a1 += sc[1024 + k] * wv;
;     }
	v_pk_fma_f32 v[6:7], v[136:137], v[42:43], v[6:7] op_sel_hi:[0,1,1]
	s_waitcnt vmcnt(29)
	v_pk_fma_f32 v[6:7], v[138:139], v[60:61], v[6:7] op_sel_hi:[0,1,1]
	s_waitcnt vmcnt(28)
	v_pk_fma_f32 v[6:7], v[140:141], v[44:45], v[6:7] op_sel_hi:[0,1,1]
	s_waitcnt vmcnt(27)
	v_pk_fma_f32 v[6:7], v[142:143], v[62:63], v[6:7] op_sel_hi:[0,1,1]
	s_waitcnt vmcnt(26)
	v_pk_fma_f32 v[6:7], v[144:145], v[46:47], v[6:7] op_sel_hi:[0,1,1]
	s_waitcnt vmcnt(25)
	v_pk_fma_f32 v[6:7], v[146:147], v[64:65], v[6:7] op_sel_hi:[0,1,1]
	s_waitcnt vmcnt(24)
	v_pk_fma_f32 v[6:7], v[148:149], v[48:49], v[6:7] op_sel_hi:[0,1,1]
	v_add_u32_e32 v27, 0x1000, v25
	ds_read2_b32 v[42:43], v25 offset1:8
	ds_read2_b32 v[44:45], v25 offset0:16 offset1:24
	ds_read2_b32 v[46:47], v25 offset0:32 offset1:40
	ds_read2_b32 v[48:49], v25 offset0:48 offset1:56
	ds_read2_b32 v[50:51], v27 offset1:8
	ds_read2_b32 v[52:53], v27 offset0:16 offset1:24
	ds_read2_b32 v[54:55], v27 offset0:32 offset1:40
	ds_read2_b32 v[56:57], v27 offset0:48 offset1:56
	v_add_u32_e32 v25, 0x100, v25
	s_waitcnt lgkmcnt(0)
	v_mov_b32_e32 v59, v42
	v_mov_b32_e32 v58, v50
	v_mov_b32_e32 v42, v51
	v_mov_b32_e32 v61, v44
	v_mov_b32_e32 v60, v52
	v_mov_b32_e32 v44, v53
	v_mov_b32_e32 v63, v46
	v_mov_b32_e32 v62, v54
	v_mov_b32_e32 v46, v55
	v_mov_b32_e32 v65, v48
	v_mov_b32_e32 v64, v56
	v_mov_b32_e32 v48, v57
	s_waitcnt vmcnt(23)
	v_pk_fma_f32 v[6:7], v[150:151], v[58:59], v[6:7] op_sel_hi:[0,1,1]
	s_waitcnt vmcnt(22)
	v_pk_fma_f32 v[6:7], v[152:153], v[42:43], v[6:7] op_sel_hi:[0,1,1]
	s_waitcnt vmcnt(21)
	v_pk_fma_f32 v[6:7], v[154:155], v[60:61], v[6:7] op_sel_hi:[0,1,1]
	s_waitcnt vmcnt(20)
	v_pk_fma_f32 v[6:7], v[156:157], v[44:45], v[6:7] op_sel_hi:[0,1,1]
	s_waitcnt vmcnt(19)
	v_pk_fma_f32 v[6:7], v[158:159], v[62:63], v[6:7] op_sel_hi:[0,1,1]
	s_waitcnt vmcnt(18)
	v_pk_fma_f32 v[6:7], v[160:161], v[46:47], v[6:7] op_sel_hi:[0,1,1]
	s_waitcnt vmcnt(17)
	v_pk_fma_f32 v[6:7], v[162:163], v[64:65], v[6:7] op_sel_hi:[0,1,1]
	s_waitcnt vmcnt(16)
	v_pk_fma_f32 v[6:7], v[164:165], v[48:49], v[6:7] op_sel_hi:[0,1,1]
	v_add_u32_e32 v27, 0x1000, v25
	ds_read2_b32 v[42:43], v25 offset1:8
	ds_read2_b32 v[44:45], v25 offset0:16 offset1:24
	ds_read2_b32 v[46:47], v25 offset0:32 offset1:40
	ds_read2_b32 v[48:49], v25 offset0:48 offset1:56
	ds_read2_b32 v[50:51], v27 offset1:8
	ds_read2_b32 v[52:53], v27 offset0:16 offset1:24
	ds_read2_b32 v[54:55], v27 offset0:32 offset1:40
	ds_read2_b32 v[56:57], v27 offset0:48 offset1:56
	v_add_u32_e32 v25, 0x100, v25
	s_waitcnt lgkmcnt(0)
	v_mov_b32_e32 v59, v42
	v_mov_b32_e32 v58, v50
	v_mov_b32_e32 v42, v51
	v_mov_b32_e32 v61, v44
	v_mov_b32_e32 v60, v52
	v_mov_b32_e32 v44, v53
	v_mov_b32_e32 v63, v46
	v_mov_b32_e32 v62, v54
	v_mov_b32_e32 v46, v55
	v_mov_b32_e32 v65, v48
	v_mov_b32_e32 v64, v56
	v_mov_b32_e32 v48, v57
	s_waitcnt vmcnt(15)
	v_pk_fma_f32 v[6:7], v[166:167], v[58:59], v[6:7] op_sel_hi:[0,1,1]
	s_waitcnt vmcnt(14)
	v_pk_fma_f32 v[6:7], v[168:169], v[42:43], v[6:7] op_sel_hi:[0,1,1]
	s_waitcnt vmcnt(13)
	v_pk_fma_f32 v[6:7], v[170:171], v[60:61], v[6:7] op_sel_hi:[0,1,1]
	s_waitcnt vmcnt(12)
	v_pk_fma_f32 v[6:7], v[172:173], v[44:45], v[6:7] op_sel_hi:[0,1,1]
	s_waitcnt vmcnt(11)
	v_pk_fma_f32 v[6:7], v[174:175], v[62:63], v[6:7] op_sel_hi:[0,1,1]
	s_waitcnt vmcnt(10)
	v_pk_fma_f32 v[6:7], v[176:177], v[46:47], v[6:7] op_sel_hi:[0,1,1]
	s_waitcnt vmcnt(9)
	v_pk_fma_f32 v[6:7], v[178:179], v[64:65], v[6:7] op_sel_hi:[0,1,1]
	s_waitcnt vmcnt(8)
	v_pk_fma_f32 v[6:7], v[180:181], v[48:49], v[6:7] op_sel_hi:[0,1,1]
	v_add_u32_e32 v27, 0x1000, v25
	ds_read2_b32 v[42:43], v25 offset1:8
	ds_read2_b32 v[44:45], v25 offset0:16 offset1:24
	ds_read2_b32 v[46:47], v25 offset0:32 offset1:40
	ds_read2_b32 v[48:49], v25 offset0:48 offset1:56
	ds_read2_b32 v[50:51], v27 offset1:8
	ds_read2_b32 v[52:53], v27 offset0:16 offset1:24
	ds_read2_b32 v[54:55], v27 offset0:32 offset1:40
	ds_read2_b32 v[56:57], v27 offset0:48 offset1:56
	v_add_u32_e32 v25, 0x100, v25
	s_waitcnt lgkmcnt(0)
	v_mov_b32_e32 v59, v42
	v_mov_b32_e32 v58, v50
	v_mov_b32_e32 v42, v51
	v_mov_b32_e32 v61, v44
	v_mov_b32_e32 v60, v52
	v_mov_b32_e32 v44, v53
	v_mov_b32_e32 v63, v46
	v_mov_b32_e32 v62, v54
	v_mov_b32_e32 v46, v55
	v_mov_b32_e32 v65, v48
	v_mov_b32_e32 v64, v56
	v_mov_b32_e32 v48, v57
	s_waitcnt vmcnt(7)
	v_pk_fma_f32 v[6:7], v[182:183], v[58:59], v[6:7] op_sel_hi:[0,1,1]
	s_waitcnt vmcnt(6)
	v_pk_fma_f32 v[6:7], v[184:185], v[42:43], v[6:7] op_sel_hi:[0,1,1]
	s_waitcnt vmcnt(5)
	v_pk_fma_f32 v[6:7], v[186:187], v[60:61], v[6:7] op_sel_hi:[0,1,1]
	s_waitcnt vmcnt(4)
	v_pk_fma_f32 v[6:7], v[190:191], v[44:45], v[6:7] op_sel_hi:[0,1,1]
	s_waitcnt vmcnt(3)
	v_pk_fma_f32 v[6:7], v[192:193], v[62:63], v[6:7] op_sel_hi:[0,1,1]
	s_waitcnt vmcnt(2)
	v_pk_fma_f32 v[6:7], v[194:195], v[46:47], v[6:7] op_sel_hi:[0,1,1]
	s_waitcnt vmcnt(1)
	v_pk_fma_f32 v[6:7], v[196:197], v[64:65], v[6:7] op_sel_hi:[0,1,1]
	s_waitcnt vmcnt(0)
	v_pk_fma_f32 v[6:7], v[198:199], v[48:49], v[6:7] op_sel_hi:[0,1,1]
	s_andn2_b64 exec, exec, s[16:17]
	s_cbranch_execnz .LBB0_58
	s_or_b64 exec, exec, s[16:17]
